# P6 mlstm_out: 16 serialized BC loads hoisted into 4 dwordx4, second BW load issued with the first
# speedup vs baseline: 1.0009x; 1.0009x over previous
; #define LAS __attribute__((address_space(3)))
; __device__ __forceinline__ unsigned cvt_pk_bf16(float lo, float hi) { unsigned r; asm volatile("v_cvt_pk_bf16_f32 %0, %1, %2" : "=v"(r) : "v"(lo), "v"(hi)); return r; }
; __device__ __forceinline__ void mlstm_out_unit(const Frame& F, int c, int h, int tb) {
;     ...
;         {
;             const int tt = w >> 1; f32x4 sacc[2]; sacc[0] = (f32x4){0.f, 0.f, 0.f, 0.f}; sacc[1] = sacc[0];
; #pragma unroll 2
;             for (int ks = 0; ks < 8; ++ks) { const bf16x8 qf = *(const LAS bf16x8*)(Qs + (tt * 16 + fr) * 264 + ks * 32 + kg * 8);
; #pragma unroll
;                 for (int x = 0; x < 2; ++x) { const bf16x8 kf = *(const LAS bf16x8*)(Ks + (((w & 1) * 2 + x) * 16 + fr) * 264 + ks * 32 + kg * 8);
;                     sacc[x] = __builtin_amdgcn_mfma_f32_16x16x32_bf16(qf, kf, sacc[x], 0, 0, 0); } }
;             float rs[4] = {0.f, 0.f, 0.f, 0.f};
; #pragma unroll
;             for (int x = 0; x < 2; ++x) { const int sl = ((w & 1) * 2 + x) * 16 + fr; const float ws = BW[s0 + sl];
; #pragma unroll
;                 for (int j = 0; j < 4; ++j) { const int tl = tt * 16 + kg * 4 + j; const bool ok = (s0 + sl) <= (t0 + tl);
;                     const float pv = ok ? sacc[x][j] * 0.0625f * expf(ws - sMr[tl]) : 0.f; rs[j] += pv;
;                     Ps[tl * 72 + sl] = (bf16_t)(cvt_pk_bf16(pv, 0.f) & 0xffff); } }
.LBB0_750:
	v_add_u32_e32 v74, s8, v196
	v_add_u32_e32 v85, s8, v195
	ds_read_b128 v[214:217], v74
	ds_read_b128 v[218:221], v85
	ds_read_b128 v[222:225], v74 offset:64
	ds_read_b128 v[226:229], v85 offset:64
	s_addk_i32 s8, 0x80
	s_waitcnt lgkmcnt(2)
	v_mfma_f32_16x16x32_bf16 v[68:71], v[214:217], v[218:221], v[68:71]
	ds_read_b128 v[218:221], v85 offset:8448
	ds_read_b128 v[230:233], v85 offset:8512
	s_cmpk_eq_i32 s8, 0x200
	s_waitcnt lgkmcnt(1)
	v_mfma_f32_16x16x32_bf16 v[64:67], v[214:217], v[218:221], v[64:67]
	v_mfma_f32_16x16x32_bf16 v[68:71], v[222:225], v[226:229], v[68:71]
	s_waitcnt lgkmcnt(0)
	v_mfma_f32_16x16x32_bf16 v[64:67], v[222:225], v[230:233], v[64:67]
	s_cbranch_scc0 .LBB0_750
	s_add_i32 s8, s18, s29
	v_or_b32_e32 v74, s8, v108
	v_lshl_add_u64 v[214:215], v[74:75], 2, s[16:17]
	global_load_dword v91, v[214:215], off
	global_load_dword v243, v[214:215], off offset:64
	v_cmp_le_i32_e32 vcc, v74, v89
	v_mov_b32_e32 v85, 0
	v_mov_b32_e32 v87, 0
	s_and_saveexec_b64 s[18:19], vcc
	s_cbranch_execz .LBB0_753
	ds_read_b32 v87, v111
	v_mul_f32_e32 v68, 0x3d800000, v68
	s_waitcnt vmcnt(0) lgkmcnt(0)
	v_sub_f32_e32 v87, v91, v87
	v_mul_f32_e32 v214, 0x3fb8aa3b, v87
	v_fma_f32 v215, v87, s36, -v214
	v_rndne_f32_e32 v216, v214
	v_fmac_f32_e32 v215, 0x32a5705f, v87
	v_sub_f32_e32 v214, v214, v216
	v_add_f32_e32 v214, v214, v215
	v_cvt_i32_f32_e32 v216, v216
	v_exp_f32_e32 v214, v214
	v_cmp_ngt_f32_e32 vcc, s37, v87
	v_ldexp_f32 v214, v214, v216
	s_nop 0
	v_cndmask_b32_e32 v214, 0, v214, vcc
	v_cmp_nlt_f32_e32 vcc, s38, v87
	s_nop 1
	v_cndmask_b32_e32 v87, v209, v214, vcc
	v_mul_f32_e32 v87, v68, v87

; __device__ __forceinline__ unsigned cvt_pk_bf16(float lo, float hi) { unsigned r; asm volatile("v_cvt_pk_bf16_f32 %0, %1, %2" : "=v"(r) : "v"(lo), "v"(hi)); return r; }
; __device__ __forceinline__ void mlstm_out_unit(const Frame& F, int c, int h, int tb) {
;     ...
;             for (int x = 0; x < 2; ++x) { const int sl = ((w & 1) * 2 + x) * 16 + fr; const float ws = BW[s0 + sl];
; #pragma unroll
;                 for (int j = 0; j < 4; ++j) { const int tl = tt * 16 + kg * 4 + j; const bool ok = (s0 + sl) <= (t0 + tl);
;                     const float pv = ok ? sacc[x][j] * 0.0625f * expf(ws - sMr[tl]) : 0.f; rs[j] += pv;
;                     Ps[tl * 72 + sl] = (bf16_t)(cvt_pk_bf16(pv, 0.f) & 0xffff); } }
.LBB0_759:
	s_or_b64 exec, exec, s[18:19]
	v_add_u32_e32 v74, s8, v108
	v_lshl_add_u64 v[70:71], v[74:75], 2, s[16:17]
	s_waitcnt vmcnt(0)
	v_cvt_pk_bf16_f32 v91, v68, v75
	v_mov_b32_e32 v71, v243
	v_add_u32_e32 v70, v110, v121
	ds_write_b16 v70, v91
	v_or_b32_e32 v91, s8, v109
	v_cmp_le_i32_e32 vcc, v91, v89
	v_mov_b32_e32 v70, 0
	v_mov_b32_e32 v74, 0
	s_and_saveexec_b64 s[18:19], vcc
	s_cbranch_execz .LBB0_761
	ds_read_b32 v74, v111
	v_mul_f32_e32 v64, 0x3d800000, v64
	s_waitcnt vmcnt(0) lgkmcnt(0)
	v_sub_f32_e32 v74, v71, v74
	v_mul_f32_e32 v214, 0x3fb8aa3b, v74
	v_fma_f32 v215, v74, s36, -v214
	v_rndne_f32_e32 v216, v214
	v_fmac_f32_e32 v215, 0x32a5705f, v74
	v_sub_f32_e32 v214, v214, v216
	v_add_f32_e32 v214, v214, v215
	v_cvt_i32_f32_e32 v216, v216
	v_exp_f32_e32 v214, v214
	v_cmp_ngt_f32_e32 vcc, s37, v74
	v_ldexp_f32 v214, v214, v216
	s_nop 0
	v_cndmask_b32_e32 v214, 0, v214, vcc
	v_cmp_nlt_f32_e32 vcc, s38, v74
	s_nop 1
	v_cndmask_b32_e32 v74, v209, v214, vcc
	v_mul_f32_e32 v74, v64, v74

; __device__ __forceinline__ void lds_add(LAS float* p, float v) { __hip_atomic_fetch_add(p, v, __ATOMIC_RELAXED, __HIP_MEMORY_SCOPE_WORKGROUP); }
; __device__ __forceinline__ void mlstm_out_unit(const Frame& F, int c, int h, int tb) {
;     ...
;     for (int tt = 0; tt < 4; ++tt)
; #pragma unroll
;         for (int j = 0; j < 4; ++j) { const int tl = tt * 16 + kg * 4 + j; const float mt = BC[t0 + tl] + sMr[tl]; const float dn = 1.f / fmaxf(fabsf(sDen[tl]), expf(-mt));
;             acc[tt][0][j] *= dn; acc[tt][1][j] *= dn; float q = acc[tt][0][j] * acc[tt][0][j] + acc[tt][1][j] * acc[tt][1][j];
;             q += __shfl_xor(q, 1); q += __shfl_xor(q, 2); q += __shfl_xor(q, 4); q += __shfl_xor(q, 8);
;             if (fr == 0) lds_add(&sSq[tl], q); }
.LBB0_775:
	s_add_u32 s16, s20, s49
	s_addc_u32 s17, s21, 0
	v_or_b32_e32 v74, s47, v106
	v_lshl_add_u64 v[24:25], v[74:75], 2, s[16:17]
	global_load_dwordx4 v[216:219], v[24:25], off
	global_load_dwordx4 v[220:223], v[24:25], off offset:64
	global_load_dwordx4 v[224:227], v[24:25], off offset:128
	global_load_dwordx4 v[228:231], v[24:25], off offset:192
	ds_read_b32 v25, v126
	ds_read_b32 v26, v127
	s_waitcnt lgkmcnt(0)
	v_max_f32_e64 v26, |v26|, |v26|
	s_waitcnt vmcnt(0)
	v_add_f32_e32 v24, v216, v25
	v_mul_f32_e32 v25, 0xbfb8aa3b, v24
	v_fma_f32 v27, v24, s42, -v25
	v_rndne_f32_e32 v28, v25
	v_fmac_f32_e32 v27, 0xb2a5705f, v24
	v_sub_f32_e32 v25, v25, v28
	v_add_f32_e32 v25, v25, v27
	v_cvt_i32_f32_e32 v28, v28
	v_exp_f32_e32 v25, v25
	v_cmp_nlt_f32_e32 vcc, s43, v24
	v_ldexp_f32 v25, v25, v28
	s_nop 0
	v_cndmask_b32_e32 v25, 0, v25, vcc
	v_cmp_ngt_f32_e32 vcc, s44, v24
	s_nop 1
	v_cndmask_b32_e32 v24, v209, v25, vcc
	v_max_f32_e32 v24, v26, v24
	v_div_scale_f32 v25, s[18:19], v24, v24, 1.0
	v_rcp_f32_e32 v26, v25
	v_div_scale_f32 v27, vcc, 1.0, v24, 1.0
	v_fma_f32 v28, -v25, v26, 1.0
	v_fmac_f32_e32 v26, v28, v26
	v_mul_f32_e32 v28, v27, v26
	v_fma_f32 v29, -v25, v28, v27
	v_fmac_f32_e32 v28, v29, v26
	v_fma_f32 v25, -v25, v28, v27
	v_div_fmas_f32 v25, v25, v26, v28
	v_div_fixup_f32 v24, v25, v24, 1.0
	v_mul_f32_e32 v32, v60, v24
	v_mul_f32_e32 v38, v56, v24
	v_mul_f32_e32 v24, v32, v32
	v_fmac_f32_e32 v24, v38, v38
	ds_bpermute_b32 v25, v73, v24
	s_waitcnt lgkmcnt(0)
	v_add_f32_e32 v24, v24, v25
	ds_bpermute_b32 v25, v92, v24
	s_waitcnt lgkmcnt(0)
	v_add_f32_e32 v24, v24, v25
	ds_bpermute_b32 v25, v93, v24
	s_waitcnt lgkmcnt(0)
	v_add_f32_e32 v24, v24, v25
	ds_bpermute_b32 v25, v94, v24
	s_and_saveexec_b64 s[18:19], s[4:5]
	s_cbranch_execz .LBB0_777
	s_waitcnt lgkmcnt(0)
	v_add_f32_e32 v24, v24, v25
	ds_add_f32 v128, v24
.LBB0_777:
	s_or_b64 exec, exec, s[18:19]
	v_add_u32_e32 v24, s47, v106
	s_waitcnt lgkmcnt(0)
	v_mov_b32_e32 v25, v75
	v_lshl_add_u64 v[24:25], v[24:25], 2, s[16:17]
	v_mov_b32_e32 v26, v217
	ds_read_b32 v27, v130
	ds_read_b32 v28, v131
	s_waitcnt lgkmcnt(0)
	v_max_f32_e64 v28, |v28|, |v28|
	s_waitcnt vmcnt(0)
	v_add_f32_e32 v26, v26, v27
	v_mul_f32_e32 v27, 0xbfb8aa3b, v26
	v_fma_f32 v29, v26, s42, -v27
	v_rndne_f32_e32 v30, v27
	v_fmac_f32_e32 v29, 0xb2a5705f, v26
	v_sub_f32_e32 v27, v27, v30
	v_add_f32_e32 v27, v27, v29
	v_cvt_i32_f32_e32 v30, v30
	v_exp_f32_e32 v27, v27
	v_cmp_nlt_f32_e32 vcc, s43, v26
	v_ldexp_f32 v27, v27, v30
	s_nop 0
	v_cndmask_b32_e32 v27, 0, v27, vcc
	v_cmp_ngt_f32_e32 vcc, s44, v26
	s_nop 1
	v_cndmask_b32_e32 v26, v209, v27, vcc
	v_max_f32_e32 v26, v28, v26
	v_div_scale_f32 v27, s[16:17], v26, v26, 1.0
	v_rcp_f32_e32 v28, v27
	v_div_scale_f32 v29, vcc, 1.0, v26, 1.0
	v_fma_f32 v30, -v27, v28, 1.0
	v_fmac_f32_e32 v28, v30, v28
	v_mul_f32_e32 v30, v29, v28
	v_fma_f32 v31, -v27, v30, v29
	v_fmac_f32_e32 v30, v31, v28
	v_fma_f32 v27, -v27, v30, v29
	v_div_fmas_f32 v27, v27, v28, v30
	v_div_fixup_f32 v26, v27, v26, 1.0
	v_mul_f32_e32 v31, v61, v26
	v_mul_f32_e32 v37, v57, v26
	v_mul_f32_e32 v26, v31, v31
	v_fmac_f32_e32 v26, v37, v37
	ds_bpermute_b32 v27, v73, v26
	s_waitcnt lgkmcnt(0)
	v_add_f32_e32 v26, v26, v27
	ds_bpermute_b32 v27, v92, v26
	s_waitcnt lgkmcnt(0)
	v_add_f32_e32 v26, v26, v27
	ds_bpermute_b32 v27, v93, v26
	s_waitcnt lgkmcnt(0)
	v_add_f32_e32 v26, v26, v27
	ds_bpermute_b32 v27, v94, v26
	s_and_saveexec_b64 s[16:17], s[4:5]
	s_cbranch_execz .LBB0_779
	s_waitcnt lgkmcnt(0)
	v_add_f32_e32 v26, v26, v27
	ds_add_f32 v132, v26
.LBB0_779:
	s_or_b64 exec, exec, s[16:17]
	v_mov_b32_e32 v26, v218
	s_waitcnt lgkmcnt(0)
	ds_read_b32 v27, v134
	ds_read_b32 v28, v135
	s_waitcnt lgkmcnt(0)
	v_max_f32_e64 v28, |v28|, |v28|
	s_waitcnt vmcnt(0)
	v_add_f32_e32 v26, v26, v27
	v_mul_f32_e32 v27, 0xbfb8aa3b, v26
	v_fma_f32 v29, v26, s42, -v27
	v_rndne_f32_e32 v30, v27
	v_fmac_f32_e32 v29, 0xb2a5705f, v26
	v_sub_f32_e32 v27, v27, v30
	v_add_f32_e32 v27, v27, v29
	v_cvt_i32_f32_e32 v30, v30
	v_exp_f32_e32 v27, v27
	v_cmp_nlt_f32_e32 vcc, s43, v26
	v_ldexp_f32 v27, v27, v30
	s_nop 0
	v_cndmask_b32_e32 v27, 0, v27, vcc
	v_cmp_ngt_f32_e32 vcc, s44, v26
	s_nop 1
	v_cndmask_b32_e32 v26, v209, v27, vcc
	v_max_f32_e32 v26, v28, v26
	v_div_scale_f32 v27, s[16:17], v26, v26, 1.0
	v_rcp_f32_e32 v28, v27
	v_div_scale_f32 v29, vcc, 1.0, v26, 1.0
	v_fma_f32 v30, -v27, v28, 1.0
	v_fmac_f32_e32 v28, v30, v28
	v_mul_f32_e32 v30, v29, v28
	v_fma_f32 v33, -v27, v30, v29
	v_fmac_f32_e32 v30, v33, v28
	v_fma_f32 v27, -v27, v30, v29
	v_div_fmas_f32 v27, v27, v28, v30
	v_div_fixup_f32 v26, v27, v26, 1.0
	v_mul_f32_e32 v29, v62, v26
	v_mul_f32_e32 v36, v58, v26
	v_mul_f32_e32 v26, v29, v29
	v_fmac_f32_e32 v26, v36, v36
	ds_bpermute_b32 v27, v73, v26
	s_waitcnt lgkmcnt(0)
	v_add_f32_e32 v26, v26, v27
	ds_bpermute_b32 v27, v92, v26
	s_waitcnt lgkmcnt(0)
	v_add_f32_e32 v26, v26, v27
	ds_bpermute_b32 v27, v93, v26
	s_waitcnt lgkmcnt(0)
	v_add_f32_e32 v26, v26, v27
	ds_bpermute_b32 v27, v94, v26
	s_and_saveexec_b64 s[16:17], s[4:5]
	s_cbranch_execz .LBB0_781
	s_waitcnt lgkmcnt(0)
	v_add_f32_e32 v26, v26, v27
	ds_add_f32 v136, v26
; __device__ __forceinline__ void lds_add(LAS float* p, float v) { __hip_atomic_fetch_add(p, v, __ATOMIC_RELAXED, __HIP_MEMORY_SCOPE_WORKGROUP); }
; __device__ __forceinline__ void mlstm_out_unit(const Frame& F, int c, int h, int tb) {
;     ...
;     for (int tt = 0; tt < 4; ++tt)
; #pragma unroll
;         for (int j = 0; j < 4; ++j) { const int tl = tt * 16 + kg * 4 + j; const float mt = BC[t0 + tl] + sMr[tl]; const float dn = 1.f / fmaxf(fabsf(sDen[tl]), expf(-mt));
;             acc[tt][0][j] *= dn; acc[tt][1][j] *= dn; float q = acc[tt][0][j] * acc[tt][0][j] + acc[tt][1][j] * acc[tt][1][j];
;             q += __shfl_xor(q, 1); q += __shfl_xor(q, 2); q += __shfl_xor(q, 4); q += __shfl_xor(q, 8);
;             if (fr == 0) lds_add(&sSq[tl], q); }
.LBB0_781:
	s_or_b64 exec, exec, s[16:17]
	v_mov_b32_e32 v26, v219
	s_waitcnt lgkmcnt(0)
	ds_read_b32 v27, v138
	ds_read_b32 v28, v139
	s_waitcnt lgkmcnt(0)
	v_max_f32_e64 v28, |v28|, |v28|
	s_waitcnt vmcnt(0)
	v_add_f32_e32 v26, v26, v27
	v_mul_f32_e32 v27, 0xbfb8aa3b, v26
	v_fma_f32 v30, v26, s42, -v27
	v_rndne_f32_e32 v33, v27
	v_fmac_f32_e32 v30, 0xb2a5705f, v26
	v_sub_f32_e32 v27, v27, v33
	v_add_f32_e32 v27, v27, v30
	v_cvt_i32_f32_e32 v33, v33
	v_exp_f32_e32 v27, v27
	v_cmp_nlt_f32_e32 vcc, s43, v26
	v_ldexp_f32 v27, v27, v33
	s_nop 0
	v_cndmask_b32_e32 v27, 0, v27, vcc
	v_cmp_ngt_f32_e32 vcc, s44, v26
	s_nop 1
	v_cndmask_b32_e32 v26, v209, v27, vcc
	v_max_f32_e32 v26, v28, v26
	v_div_scale_f32 v27, s[16:17], v26, v26, 1.0
	v_rcp_f32_e32 v28, v27
	v_div_scale_f32 v30, vcc, 1.0, v26, 1.0
	v_fma_f32 v33, -v27, v28, 1.0
	v_fmac_f32_e32 v28, v33, v28
	v_mul_f32_e32 v33, v30, v28
	v_fma_f32 v34, -v27, v33, v30
	v_fmac_f32_e32 v33, v34, v28
	v_fma_f32 v27, -v27, v33, v30
	v_div_fmas_f32 v27, v27, v28, v33
	v_div_fixup_f32 v26, v27, v26, 1.0
	v_mul_f32_e32 v27, v63, v26
	v_mul_f32_e32 v35, v59, v26
	v_mul_f32_e32 v26, v27, v27
	v_fmac_f32_e32 v26, v35, v35
	ds_bpermute_b32 v28, v73, v26
	s_waitcnt lgkmcnt(0)
	v_add_f32_e32 v26, v26, v28
	ds_bpermute_b32 v28, v92, v26
	s_waitcnt lgkmcnt(0)
	v_add_f32_e32 v26, v26, v28
	ds_bpermute_b32 v28, v93, v26
	s_waitcnt lgkmcnt(0)
	v_add_f32_e32 v26, v26, v28
	ds_bpermute_b32 v28, v94, v26
	s_and_saveexec_b64 s[16:17], s[4:5]
	s_cbranch_execz .LBB0_783
	s_waitcnt lgkmcnt(0)
	v_add_f32_e32 v26, v26, v28
	ds_add_f32 v140, v26
.LBB0_783:
	s_or_b64 exec, exec, s[16:17]
	v_mov_b32_e32 v26, v220
	s_waitcnt lgkmcnt(0)
	ds_read_b32 v28, v142
	ds_read_b32 v30, v143
	s_waitcnt lgkmcnt(0)
	v_max_f32_e64 v30, |v30|, |v30|
	s_waitcnt vmcnt(0)
	v_add_f32_e32 v26, v26, v28
	v_mul_f32_e32 v28, 0xbfb8aa3b, v26
	v_fma_f32 v33, v26, s42, -v28
	v_rndne_f32_e32 v34, v28
	v_fmac_f32_e32 v33, 0xb2a5705f, v26
	v_sub_f32_e32 v28, v28, v34
	v_add_f32_e32 v28, v28, v33
	v_cvt_i32_f32_e32 v34, v34
	v_exp_f32_e32 v28, v28
	v_cmp_nlt_f32_e32 vcc, s43, v26
	v_ldexp_f32 v28, v28, v34
	s_nop 0
	v_cndmask_b32_e32 v28, 0, v28, vcc
	v_cmp_ngt_f32_e32 vcc, s44, v26
	s_nop 1
	v_cndmask_b32_e32 v26, v209, v28, vcc
	v_max_f32_e32 v26, v30, v26
	v_div_scale_f32 v28, s[16:17], v26, v26, 1.0
	v_rcp_f32_e32 v30, v28
	v_div_scale_f32 v33, vcc, 1.0, v26, 1.0
	v_fma_f32 v34, -v28, v30, 1.0
	v_fmac_f32_e32 v30, v34, v30
	v_mul_f32_e32 v34, v33, v30
	v_fma_f32 v39, -v28, v34, v33
	v_fmac_f32_e32 v34, v39, v30
	v_fma_f32 v28, -v28, v34, v33
	v_div_fmas_f32 v28, v28, v30, v34
	v_div_fixup_f32 v26, v28, v26, 1.0
	v_mul_f32_e32 v34, v16, v26
	v_mul_f32_e32 v26, v20, v26
	v_mul_f32_e32 v16, v26, v26
	v_fmac_f32_e32 v16, v34, v34
	ds_bpermute_b32 v20, v73, v16
	s_waitcnt lgkmcnt(0)
	v_add_f32_e32 v16, v16, v20
	ds_bpermute_b32 v20, v92, v16
	s_waitcnt lgkmcnt(0)
	v_add_f32_e32 v16, v16, v20
	ds_bpermute_b32 v20, v93, v16
	s_waitcnt lgkmcnt(0)
	v_add_f32_e32 v16, v16, v20
	ds_bpermute_b32 v20, v94, v16
	s_and_saveexec_b64 s[16:17], s[4:5]
	s_cbranch_execz .LBB0_785
	s_waitcnt lgkmcnt(0)
	v_add_f32_e32 v16, v16, v20
	ds_add_f32 v147, v16
.LBB0_785:
	s_or_b64 exec, exec, s[16:17]
	v_mov_b32_e32 v16, v221
	s_waitcnt lgkmcnt(0)
	ds_read_b32 v20, v151
	ds_read_b32 v28, v152
	s_waitcnt lgkmcnt(0)
	v_max_f32_e64 v28, |v28|, |v28|
	s_waitcnt vmcnt(0)
	v_add_f32_e32 v16, v16, v20
	v_mul_f32_e32 v20, 0xbfb8aa3b, v16
	v_fma_f32 v30, v16, s42, -v20
	v_rndne_f32_e32 v33, v20
	v_fmac_f32_e32 v30, 0xb2a5705f, v16
	v_sub_f32_e32 v20, v20, v33
	v_add_f32_e32 v20, v20, v30
	v_cvt_i32_f32_e32 v33, v33
	v_exp_f32_e32 v20, v20
	v_cmp_nlt_f32_e32 vcc, s43, v16
	v_ldexp_f32 v20, v20, v33
	s_nop 0
	v_cndmask_b32_e32 v20, 0, v20, vcc
	v_cmp_ngt_f32_e32 vcc, s44, v16
	s_nop 1
	v_cndmask_b32_e32 v16, v209, v20, vcc
	v_max_f32_e32 v16, v28, v16
	v_div_scale_f32 v20, s[16:17], v16, v16, 1.0
	v_rcp_f32_e32 v28, v20
	v_div_scale_f32 v30, vcc, 1.0, v16, 1.0
	v_fma_f32 v33, -v20, v28, 1.0
	v_fmac_f32_e32 v28, v33, v28
	v_mul_f32_e32 v33, v30, v28
	v_fma_f32 v39, -v20, v33, v30
	v_fmac_f32_e32 v33, v39, v28
	v_fma_f32 v20, -v20, v33, v30
	v_div_fmas_f32 v20, v20, v28, v33
	v_div_fixup_f32 v16, v20, v16, 1.0
	v_mul_f32_e32 v21, v21, v16
	v_mul_f32_e32 v33, v17, v16
	v_mul_f32_e32 v16, v21, v21
	v_fmac_f32_e32 v16, v33, v33
	ds_bpermute_b32 v17, v73, v16
	s_waitcnt lgkmcnt(0)
	v_add_f32_e32 v16, v16, v17
	ds_bpermute_b32 v17, v92, v16
	s_waitcnt lgkmcnt(0)
	v_add_f32_e32 v16, v16, v17
	ds_bpermute_b32 v17, v93, v16
	s_waitcnt lgkmcnt(0)
	v_add_f32_e32 v16, v16, v17
	ds_bpermute_b32 v17, v94, v16
	s_and_saveexec_b64 s[16:17], s[4:5]
	s_cbranch_execz .LBB0_787
	s_waitcnt lgkmcnt(0)
	v_add_f32_e32 v16, v16, v17
	ds_add_f32 v153, v16
.LBB0_787:
	s_or_b64 exec, exec, s[16:17]
	v_mov_b32_e32 v16, v222
	s_waitcnt lgkmcnt(0)
	ds_read_b32 v17, v155
	ds_read_b32 v20, v156
	s_waitcnt lgkmcnt(0)
	v_max_f32_e64 v20, |v20|, |v20|
	s_waitcnt vmcnt(0)
	v_add_f32_e32 v16, v16, v17
	v_mul_f32_e32 v17, 0xbfb8aa3b, v16
	v_fma_f32 v28, v16, s42, -v17
	v_rndne_f32_e32 v30, v17
	v_fmac_f32_e32 v28, 0xb2a5705f, v16
	v_sub_f32_e32 v17, v17, v30
	v_add_f32_e32 v17, v17, v28
	v_cvt_i32_f32_e32 v30, v30
	v_exp_f32_e32 v17, v17
	v_cmp_nlt_f32_e32 vcc, s43, v16
	v_ldexp_f32 v17, v17, v30
	s_nop 0
	v_cndmask_b32_e32 v17, 0, v17, vcc
	v_cmp_ngt_f32_e32 vcc, s44, v16
	s_nop 1
	v_cndmask_b32_e32 v16, v209, v17, vcc
	v_max_f32_e32 v16, v20, v16
	v_div_scale_f32 v17, s[16:17], v16, v16, 1.0
	v_rcp_f32_e32 v20, v17
	v_div_scale_f32 v28, vcc, 1.0, v16, 1.0
	v_fma_f32 v30, -v17, v20, 1.0
	v_fmac_f32_e32 v20, v30, v20
	v_mul_f32_e32 v30, v28, v20
	v_fma_f32 v39, -v17, v30, v28
	v_fmac_f32_e32 v30, v39, v20
	v_fma_f32 v17, -v17, v30, v28
	v_div_fmas_f32 v17, v17, v20, v30
	v_div_fixup_f32 v16, v17, v16, 1.0
	v_mul_f32_e32 v20, v22, v16
	v_mul_f32_e32 v30, v18, v16
	v_mul_f32_e32 v16, v20, v20
	v_fmac_f32_e32 v16, v30, v30
	ds_bpermute_b32 v17, v73, v16
	s_waitcnt lgkmcnt(0)
	v_add_f32_e32 v16, v16, v17
	ds_bpermute_b32 v17, v92, v16
	s_waitcnt lgkmcnt(0)
	v_add_f32_e32 v16, v16, v17
	ds_bpermute_b32 v17, v93, v16
	s_waitcnt lgkmcnt(0)
	v_add_f32_e32 v16, v16, v17
	ds_bpermute_b32 v17, v94, v16
	s_and_saveexec_b64 s[16:17], s[4:5]
	s_cbranch_execz .LBB0_789
	s_waitcnt lgkmcnt(0)
	v_add_f32_e32 v16, v16, v17
	ds_add_f32 v157, v16
; __device__ __forceinline__ void lds_add(LAS float* p, float v) { __hip_atomic_fetch_add(p, v, __ATOMIC_RELAXED, __HIP_MEMORY_SCOPE_WORKGROUP); }
; __device__ __forceinline__ void mlstm_out_unit(const Frame& F, int c, int h, int tb) {
;     ...
;     for (int tt = 0; tt < 4; ++tt)
; #pragma unroll
;         for (int j = 0; j < 4; ++j) { const int tl = tt * 16 + kg * 4 + j; const float mt = BC[t0 + tl] + sMr[tl]; const float dn = 1.f / fmaxf(fabsf(sDen[tl]), expf(-mt));
;             acc[tt][0][j] *= dn; acc[tt][1][j] *= dn; float q = acc[tt][0][j] * acc[tt][0][j] + acc[tt][1][j] * acc[tt][1][j];
;             q += __shfl_xor(q, 1); q += __shfl_xor(q, 2); q += __shfl_xor(q, 4); q += __shfl_xor(q, 8);
;             if (fr == 0) lds_add(&sSq[tl], q); }
.LBB0_789:
	s_or_b64 exec, exec, s[16:17]
	v_mov_b32_e32 v16, v223
	s_waitcnt lgkmcnt(0)
	ds_read_b32 v17, v159
	ds_read_b32 v18, v161
	s_waitcnt lgkmcnt(0)
	v_max_f32_e64 v18, |v18|, |v18|
	s_waitcnt vmcnt(0)
	v_add_f32_e32 v16, v16, v17
	v_mul_f32_e32 v17, 0xbfb8aa3b, v16
	v_fma_f32 v22, v16, s42, -v17
	v_rndne_f32_e32 v28, v17
	v_fmac_f32_e32 v22, 0xb2a5705f, v16
	v_sub_f32_e32 v17, v17, v28
	v_add_f32_e32 v17, v17, v22
	v_cvt_i32_f32_e32 v28, v28
	v_exp_f32_e32 v17, v17
	v_cmp_nlt_f32_e32 vcc, s43, v16
	v_ldexp_f32 v17, v17, v28
	s_nop 0
	v_cndmask_b32_e32 v17, 0, v17, vcc
	v_cmp_ngt_f32_e32 vcc, s44, v16
	s_nop 1
	v_cndmask_b32_e32 v16, v209, v17, vcc
	v_max_f32_e32 v16, v18, v16
	v_div_scale_f32 v17, s[16:17], v16, v16, 1.0
	v_rcp_f32_e32 v18, v17
	v_div_scale_f32 v22, vcc, 1.0, v16, 1.0
	v_fma_f32 v28, -v17, v18, 1.0
	v_fmac_f32_e32 v18, v28, v18
	v_mul_f32_e32 v28, v22, v18
	v_fma_f32 v39, -v17, v28, v22
	v_fmac_f32_e32 v28, v39, v18
	v_fma_f32 v17, -v17, v28, v22
	v_div_fmas_f32 v17, v17, v18, v28
	v_div_fixup_f32 v16, v17, v16, 1.0
	v_mul_f32_e32 v17, v23, v16
	v_mul_f32_e32 v28, v19, v16
	v_mul_f32_e32 v16, v17, v17
	v_fmac_f32_e32 v16, v28, v28
	ds_bpermute_b32 v18, v73, v16
	s_waitcnt lgkmcnt(0)
	v_add_f32_e32 v16, v16, v18
	ds_bpermute_b32 v18, v92, v16
	s_waitcnt lgkmcnt(0)
	v_add_f32_e32 v16, v16, v18
	ds_bpermute_b32 v18, v93, v16
	s_waitcnt lgkmcnt(0)
	v_add_f32_e32 v16, v16, v18
	ds_bpermute_b32 v18, v94, v16
	s_and_saveexec_b64 s[16:17], s[4:5]
	s_cbranch_execz .LBB0_791
	s_waitcnt lgkmcnt(0)
	v_add_f32_e32 v16, v16, v18
	ds_add_f32 v162, v16
.LBB0_791:
	s_or_b64 exec, exec, s[16:17]
	v_mov_b32_e32 v16, v224
	s_waitcnt lgkmcnt(0)
	ds_read_b32 v18, v164
	ds_read_b32 v19, v165
	s_waitcnt lgkmcnt(0)
	v_max_f32_e64 v19, |v19|, |v19|
	s_waitcnt vmcnt(0)
	v_add_f32_e32 v16, v16, v18
	v_mul_f32_e32 v18, 0xbfb8aa3b, v16
	v_fma_f32 v22, v16, s42, -v18
	v_rndne_f32_e32 v23, v18
	v_fmac_f32_e32 v22, 0xb2a5705f, v16
	v_sub_f32_e32 v18, v18, v23
	v_add_f32_e32 v18, v18, v22
	v_cvt_i32_f32_e32 v23, v23
	v_exp_f32_e32 v18, v18
	v_cmp_nlt_f32_e32 vcc, s43, v16
	v_ldexp_f32 v18, v18, v23
	s_nop 0
	v_cndmask_b32_e32 v18, 0, v18, vcc
	v_cmp_ngt_f32_e32 vcc, s44, v16
	s_nop 1
	v_cndmask_b32_e32 v16, v209, v18, vcc
	v_max_f32_e32 v16, v19, v16
	v_div_scale_f32 v18, s[16:17], v16, v16, 1.0
	v_rcp_f32_e32 v19, v18
	v_div_scale_f32 v22, vcc, 1.0, v16, 1.0
	v_fma_f32 v23, -v18, v19, 1.0
	v_fmac_f32_e32 v19, v23, v19
	v_mul_f32_e32 v23, v22, v19
	v_fma_f32 v39, -v18, v23, v22
	v_fmac_f32_e32 v23, v39, v19
	v_fma_f32 v18, -v18, v23, v22
	v_div_fmas_f32 v18, v18, v19, v23
	v_div_fixup_f32 v16, v18, v16, 1.0
	v_mul_f32_e32 v23, v8, v16
	v_mul_f32_e32 v16, v12, v16
	v_mul_f32_e32 v8, v16, v16
	v_fmac_f32_e32 v8, v23, v23
	ds_bpermute_b32 v12, v73, v8
	s_waitcnt lgkmcnt(0)
	v_add_f32_e32 v8, v8, v12
	ds_bpermute_b32 v12, v92, v8
	s_waitcnt lgkmcnt(0)
	v_add_f32_e32 v8, v8, v12
	ds_bpermute_b32 v12, v93, v8
	s_waitcnt lgkmcnt(0)
	v_add_f32_e32 v8, v8, v12
	ds_bpermute_b32 v12, v94, v8
	s_and_saveexec_b64 s[16:17], s[4:5]
	s_cbranch_execz .LBB0_793
	s_waitcnt lgkmcnt(0)
	v_add_f32_e32 v8, v8, v12
	ds_add_f32 v166, v8
.LBB0_793:
	s_or_b64 exec, exec, s[16:17]
	v_mov_b32_e32 v8, v225
	s_waitcnt lgkmcnt(0)
	ds_read_b32 v12, v168
	ds_read_b32 v18, v169
	s_waitcnt lgkmcnt(0)
	v_max_f32_e64 v18, |v18|, |v18|
	s_waitcnt vmcnt(0)
	v_add_f32_e32 v8, v8, v12
	v_mul_f32_e32 v12, 0xbfb8aa3b, v8
	v_fma_f32 v19, v8, s42, -v12
	v_rndne_f32_e32 v22, v12
	v_fmac_f32_e32 v19, 0xb2a5705f, v8
	v_sub_f32_e32 v12, v12, v22
	v_add_f32_e32 v12, v12, v19
	v_cvt_i32_f32_e32 v22, v22
	v_exp_f32_e32 v12, v12
	v_cmp_nlt_f32_e32 vcc, s43, v8
	v_ldexp_f32 v12, v12, v22
	s_nop 0
	v_cndmask_b32_e32 v12, 0, v12, vcc
	v_cmp_ngt_f32_e32 vcc, s44, v8
	s_nop 1
	v_cndmask_b32_e32 v8, v209, v12, vcc
	v_max_f32_e32 v8, v18, v8
	v_div_scale_f32 v12, s[16:17], v8, v8, 1.0
	v_rcp_f32_e32 v18, v12
	v_div_scale_f32 v19, vcc, 1.0, v8, 1.0
	v_fma_f32 v22, -v12, v18, 1.0
	v_fmac_f32_e32 v18, v22, v18
	v_mul_f32_e32 v22, v19, v18
	v_fma_f32 v39, -v12, v22, v19
	v_fmac_f32_e32 v22, v39, v18
	v_fma_f32 v12, -v12, v22, v19
	v_div_fmas_f32 v12, v12, v18, v22
	v_div_fixup_f32 v8, v12, v8, 1.0
	v_mul_f32_e32 v13, v13, v8
	v_mul_f32_e32 v22, v9, v8
	v_mul_f32_e32 v8, v13, v13
	v_fmac_f32_e32 v8, v22, v22
	ds_bpermute_b32 v9, v73, v8
	s_waitcnt lgkmcnt(0)
	v_add_f32_e32 v8, v8, v9
	ds_bpermute_b32 v9, v92, v8
	s_waitcnt lgkmcnt(0)
	v_add_f32_e32 v8, v8, v9
	ds_bpermute_b32 v9, v93, v8
	s_waitcnt lgkmcnt(0)
	v_add_f32_e32 v8, v8, v9
	ds_bpermute_b32 v9, v94, v8
	s_and_saveexec_b64 s[16:17], s[4:5]
	s_cbranch_execz .LBB0_795
	s_waitcnt lgkmcnt(0)
	v_add_f32_e32 v8, v8, v9
	ds_add_f32 v170, v8
.LBB0_795:
	s_or_b64 exec, exec, s[16:17]
	v_mov_b32_e32 v8, v226
	s_waitcnt lgkmcnt(0)
	ds_read_b32 v9, v172
	ds_read_b32 v12, v173
	s_waitcnt lgkmcnt(0)
	v_max_f32_e64 v12, |v12|, |v12|
	s_waitcnt vmcnt(0)
	v_add_f32_e32 v8, v8, v9
	v_mul_f32_e32 v9, 0xbfb8aa3b, v8
	v_fma_f32 v18, v8, s42, -v9
	v_rndne_f32_e32 v19, v9
	v_fmac_f32_e32 v18, 0xb2a5705f, v8
	v_sub_f32_e32 v9, v9, v19
	v_add_f32_e32 v9, v9, v18
	v_cvt_i32_f32_e32 v19, v19
	v_exp_f32_e32 v9, v9
	v_cmp_nlt_f32_e32 vcc, s43, v8
	v_ldexp_f32 v9, v9, v19
	s_nop 0
	v_cndmask_b32_e32 v9, 0, v9, vcc
	v_cmp_ngt_f32_e32 vcc, s44, v8
	s_nop 1
	v_cndmask_b32_e32 v8, v209, v9, vcc
	v_max_f32_e32 v8, v12, v8
	v_div_scale_f32 v9, s[16:17], v8, v8, 1.0
	v_rcp_f32_e32 v12, v9
	v_div_scale_f32 v18, vcc, 1.0, v8, 1.0
	v_fma_f32 v19, -v9, v12, 1.0
	v_fmac_f32_e32 v12, v19, v12
	v_mul_f32_e32 v19, v18, v12
	v_fma_f32 v39, -v9, v19, v18
	v_fmac_f32_e32 v19, v39, v12
	v_fma_f32 v9, -v9, v19, v18
	v_div_fmas_f32 v9, v9, v12, v19
	v_div_fixup_f32 v8, v9, v8, 1.0
	v_mul_f32_e32 v12, v14, v8
	v_mul_f32_e32 v19, v10, v8
	v_mul_f32_e32 v8, v12, v12
	v_fmac_f32_e32 v8, v19, v19
	ds_bpermute_b32 v9, v73, v8
	s_waitcnt lgkmcnt(0)
	v_add_f32_e32 v8, v8, v9
	ds_bpermute_b32 v9, v92, v8
	s_waitcnt lgkmcnt(0)
	v_add_f32_e32 v8, v8, v9
	ds_bpermute_b32 v9, v93, v8
	s_waitcnt lgkmcnt(0)
	v_add_f32_e32 v8, v8, v9
	ds_bpermute_b32 v9, v94, v8
	s_and_saveexec_b64 s[16:17], s[4:5]
	s_cbranch_execz .LBB0_797
	s_waitcnt lgkmcnt(0)
	v_add_f32_e32 v8, v8, v9
	ds_add_f32 v174, v8
; __device__ __forceinline__ void lds_add(LAS float* p, float v) { __hip_atomic_fetch_add(p, v, __ATOMIC_RELAXED, __HIP_MEMORY_SCOPE_WORKGROUP); }
; __device__ __forceinline__ void mlstm_out_unit(const Frame& F, int c, int h, int tb) {
;     ...
;     for (int tt = 0; tt < 4; ++tt)
; #pragma unroll
;         for (int j = 0; j < 4; ++j) { const int tl = tt * 16 + kg * 4 + j; const float mt = BC[t0 + tl] + sMr[tl]; const float dn = 1.f / fmaxf(fabsf(sDen[tl]), expf(-mt));
;             acc[tt][0][j] *= dn; acc[tt][1][j] *= dn; float q = acc[tt][0][j] * acc[tt][0][j] + acc[tt][1][j] * acc[tt][1][j];
;             q += __shfl_xor(q, 1); q += __shfl_xor(q, 2); q += __shfl_xor(q, 4); q += __shfl_xor(q, 8);
;             if (fr == 0) lds_add(&sSq[tl], q); }
.LBB0_797:
	s_or_b64 exec, exec, s[16:17]
	v_mov_b32_e32 v8, v227
	s_waitcnt lgkmcnt(0)
	ds_read_b32 v9, v176
	ds_read_b32 v10, v177
	s_waitcnt lgkmcnt(0)
	v_max_f32_e64 v10, |v10|, |v10|
	s_waitcnt vmcnt(0)
	v_add_f32_e32 v8, v8, v9
	v_mul_f32_e32 v9, 0xbfb8aa3b, v8
	v_fma_f32 v14, v8, s42, -v9
	v_rndne_f32_e32 v18, v9
	v_fmac_f32_e32 v14, 0xb2a5705f, v8
	v_sub_f32_e32 v9, v9, v18
	v_add_f32_e32 v9, v9, v14
	v_cvt_i32_f32_e32 v18, v18
	v_exp_f32_e32 v9, v9
	v_cmp_nlt_f32_e32 vcc, s43, v8
	v_ldexp_f32 v9, v9, v18
	s_nop 0
	v_cndmask_b32_e32 v9, 0, v9, vcc
	v_cmp_ngt_f32_e32 vcc, s44, v8
	s_nop 1
	v_cndmask_b32_e32 v8, v209, v9, vcc
	v_max_f32_e32 v8, v10, v8
	v_div_scale_f32 v9, s[16:17], v8, v8, 1.0
	v_rcp_f32_e32 v10, v9
	v_div_scale_f32 v14, vcc, 1.0, v8, 1.0
	v_fma_f32 v18, -v9, v10, 1.0
	v_fmac_f32_e32 v10, v18, v10
	v_mul_f32_e32 v18, v14, v10
	v_fma_f32 v39, -v9, v18, v14
	v_fmac_f32_e32 v18, v39, v10
	v_fma_f32 v9, -v9, v18, v14
	v_div_fmas_f32 v9, v9, v10, v18
	v_div_fixup_f32 v8, v9, v8, 1.0
	v_mul_f32_e32 v10, v15, v8
	v_mul_f32_e32 v18, v11, v8
	v_mul_f32_e32 v8, v10, v10
	v_fmac_f32_e32 v8, v18, v18
	ds_bpermute_b32 v9, v73, v8
	s_waitcnt lgkmcnt(0)
	v_add_f32_e32 v8, v8, v9
	ds_bpermute_b32 v9, v92, v8
	s_waitcnt lgkmcnt(0)
	v_add_f32_e32 v8, v8, v9
	ds_bpermute_b32 v9, v93, v8
	s_waitcnt lgkmcnt(0)
	v_add_f32_e32 v8, v8, v9
	ds_bpermute_b32 v9, v94, v8
	s_and_saveexec_b64 s[16:17], s[4:5]
	s_cbranch_execz .LBB0_799
	s_waitcnt lgkmcnt(0)
	v_add_f32_e32 v8, v8, v9
	ds_add_f32 v178, v8
.LBB0_799:
	s_or_b64 exec, exec, s[16:17]
	v_mov_b32_e32 v8, v228
	s_waitcnt lgkmcnt(0)
	ds_read_b32 v9, v180
	ds_read_b32 v11, v181
	s_waitcnt lgkmcnt(0)
	v_max_f32_e64 v11, |v11|, |v11|
	s_waitcnt vmcnt(0)
	v_add_f32_e32 v8, v8, v9
	v_mul_f32_e32 v9, 0xbfb8aa3b, v8
	v_fma_f32 v14, v8, s42, -v9
	v_rndne_f32_e32 v15, v9
	v_fmac_f32_e32 v14, 0xb2a5705f, v8
	v_sub_f32_e32 v9, v9, v15
	v_add_f32_e32 v9, v9, v14
	v_cvt_i32_f32_e32 v15, v15
	v_exp_f32_e32 v9, v9
	v_cmp_nlt_f32_e32 vcc, s43, v8
	v_ldexp_f32 v9, v9, v15
	s_nop 0
	v_cndmask_b32_e32 v9, 0, v9, vcc
	v_cmp_ngt_f32_e32 vcc, s44, v8
	s_nop 1
	v_cndmask_b32_e32 v8, v209, v9, vcc
	v_max_f32_e32 v8, v11, v8
	v_div_scale_f32 v9, s[16:17], v8, v8, 1.0
	v_rcp_f32_e32 v11, v9
	v_div_scale_f32 v14, vcc, 1.0, v8, 1.0
	v_fma_f32 v15, -v9, v11, 1.0
	v_fmac_f32_e32 v11, v15, v11
	v_mul_f32_e32 v15, v14, v11
	v_fma_f32 v39, -v9, v15, v14
	v_fmac_f32_e32 v15, v39, v11
	v_fma_f32 v9, -v9, v15, v14
	v_div_fmas_f32 v9, v9, v11, v15
	v_div_fixup_f32 v8, v9, v8, 1.0
	v_mul_f32_e32 v9, v4, v8
	v_mul_f32_e32 v15, v0, v8
	v_mul_f32_e32 v0, v9, v9
	v_fmac_f32_e32 v0, v15, v15
	ds_bpermute_b32 v4, v73, v0
	s_waitcnt lgkmcnt(0)
	v_add_f32_e32 v0, v0, v4
	ds_bpermute_b32 v4, v92, v0
	s_waitcnt lgkmcnt(0)
	v_add_f32_e32 v0, v0, v4
	ds_bpermute_b32 v4, v93, v0
	s_waitcnt lgkmcnt(0)
	v_add_f32_e32 v0, v0, v4
	ds_bpermute_b32 v4, v94, v0
	s_and_saveexec_b64 s[16:17], s[4:5]
	s_cbranch_execz .LBB0_801
	s_waitcnt lgkmcnt(0)
	v_add_f32_e32 v0, v0, v4
	ds_add_f32 v182, v0
; __device__ __forceinline__ void lds_add(LAS float* p, float v) { __hip_atomic_fetch_add(p, v, __ATOMIC_RELAXED, __HIP_MEMORY_SCOPE_WORKGROUP); }
; __device__ __forceinline__ void mlstm_out_unit(const Frame& F, int c, int h, int tb) {
;     ...
;     for (int tt = 0; tt < 4; ++tt)
; #pragma unroll
;         for (int j = 0; j < 4; ++j) { const int tl = tt * 16 + kg * 4 + j; const float mt = BC[t0 + tl] + sMr[tl]; const float dn = 1.f / fmaxf(fabsf(sDen[tl]), expf(-mt));
;             acc[tt][0][j] *= dn; acc[tt][1][j] *= dn; float q = acc[tt][0][j] * acc[tt][0][j] + acc[tt][1][j] * acc[tt][1][j];
;             q += __shfl_xor(q, 1); q += __shfl_xor(q, 2); q += __shfl_xor(q, 4); q += __shfl_xor(q, 8);
;             if (fr == 0) lds_add(&sSq[tl], q); }
.LBB0_801:
	s_or_b64 exec, exec, s[16:17]
	v_mov_b32_e32 v0, v229
	s_waitcnt lgkmcnt(0)
	ds_read_b32 v4, v184
	ds_read_b32 v8, v185
	s_waitcnt lgkmcnt(0)
	v_max_f32_e64 v8, |v8|, |v8|
	s_waitcnt vmcnt(0)
	v_add_f32_e32 v0, v0, v4
	v_mul_f32_e32 v4, 0xbfb8aa3b, v0
	v_fma_f32 v11, v0, s42, -v4
	v_rndne_f32_e32 v14, v4
	v_fmac_f32_e32 v11, 0xb2a5705f, v0
	v_sub_f32_e32 v4, v4, v14
	v_add_f32_e32 v4, v4, v11
	v_cvt_i32_f32_e32 v14, v14
	v_exp_f32_e32 v4, v4
	v_cmp_nlt_f32_e32 vcc, s43, v0
	v_ldexp_f32 v4, v4, v14
	s_nop 0
	v_cndmask_b32_e32 v4, 0, v4, vcc
	v_cmp_ngt_f32_e32 vcc, s44, v0
	s_nop 1
	v_cndmask_b32_e32 v0, v209, v4, vcc
	v_max_f32_e32 v0, v8, v0
	v_div_scale_f32 v4, s[16:17], v0, v0, 1.0
	v_rcp_f32_e32 v8, v4
	v_div_scale_f32 v11, vcc, 1.0, v0, 1.0
	v_fma_f32 v14, -v4, v8, 1.0
	v_fmac_f32_e32 v8, v14, v8
	v_mul_f32_e32 v14, v11, v8
	v_fma_f32 v39, -v4, v14, v11
	v_fmac_f32_e32 v14, v39, v8
	v_fma_f32 v4, -v4, v14, v11
	v_div_fmas_f32 v4, v4, v8, v14
	v_div_fixup_f32 v0, v4, v0, 1.0
	v_mul_f32_e32 v8, v5, v0
	v_mul_f32_e32 v14, v1, v0
	v_mul_f32_e32 v0, v8, v8
	v_fmac_f32_e32 v0, v14, v14
	ds_bpermute_b32 v1, v73, v0
	s_waitcnt lgkmcnt(0)
	v_add_f32_e32 v0, v0, v1
	ds_bpermute_b32 v1, v92, v0
	s_waitcnt lgkmcnt(0)
	v_add_f32_e32 v0, v0, v1
	ds_bpermute_b32 v1, v93, v0
	s_waitcnt lgkmcnt(0)
	v_add_f32_e32 v0, v0, v1
	ds_bpermute_b32 v1, v94, v0
	s_and_saveexec_b64 s[16:17], s[4:5]
	s_cbranch_execz .LBB0_803
	s_waitcnt lgkmcnt(0)
	v_add_f32_e32 v0, v0, v1
	ds_add_f32 v186, v0
.LBB0_803:
	s_or_b64 exec, exec, s[16:17]
	v_mov_b32_e32 v0, v230
	s_waitcnt lgkmcnt(0)
	ds_read_b32 v1, v188
	ds_read_b32 v4, v189
	s_waitcnt lgkmcnt(0)
	v_max_f32_e64 v4, |v4|, |v4|
	s_waitcnt vmcnt(0)
	v_add_f32_e32 v0, v0, v1
	v_mul_f32_e32 v1, 0xbfb8aa3b, v0
	v_fma_f32 v5, v0, s42, -v1
	v_rndne_f32_e32 v11, v1
	v_fmac_f32_e32 v5, 0xb2a5705f, v0
	v_sub_f32_e32 v1, v1, v11
	v_add_f32_e32 v1, v1, v5
	v_cvt_i32_f32_e32 v11, v11
	v_exp_f32_e32 v1, v1
	v_cmp_nlt_f32_e32 vcc, s43, v0
	v_ldexp_f32 v1, v1, v11
	s_nop 0
	v_cndmask_b32_e32 v1, 0, v1, vcc
	v_cmp_ngt_f32_e32 vcc, s44, v0
	s_nop 1
	v_cndmask_b32_e32 v0, v209, v1, vcc
	v_max_f32_e32 v0, v4, v0
	v_div_scale_f32 v1, s[16:17], v0, v0, 1.0
	v_rcp_f32_e32 v4, v1
	v_div_scale_f32 v5, vcc, 1.0, v0, 1.0
	v_fma_f32 v11, -v1, v4, 1.0
	v_fmac_f32_e32 v4, v11, v4
	v_mul_f32_e32 v11, v5, v4
	v_fma_f32 v39, -v1, v11, v5
	v_fmac_f32_e32 v11, v39, v4
	v_fma_f32 v1, -v1, v11, v5
	v_div_fmas_f32 v1, v1, v4, v11
	v_div_fixup_f32 v0, v1, v0, 1.0
	v_mul_f32_e32 v5, v6, v0
	v_mul_f32_e32 v11, v2, v0
	v_mul_f32_e32 v0, v5, v5
	v_fmac_f32_e32 v0, v11, v11
	ds_bpermute_b32 v1, v73, v0
	s_waitcnt lgkmcnt(0)
	v_add_f32_e32 v0, v0, v1
	ds_bpermute_b32 v1, v92, v0
	s_waitcnt lgkmcnt(0)
	v_add_f32_e32 v0, v0, v1
	ds_bpermute_b32 v1, v93, v0
	s_waitcnt lgkmcnt(0)
	v_add_f32_e32 v0, v0, v1
	ds_bpermute_b32 v1, v94, v0
	s_and_saveexec_b64 s[16:17], s[4:5]
	s_cbranch_execz .LBB0_805
	s_waitcnt lgkmcnt(0)
	v_add_f32_e32 v0, v0, v1
	ds_add_f32 v190, v0
.LBB0_805:
	s_or_b64 exec, exec, s[16:17]
	v_mov_b32_e32 v0, v231
	s_waitcnt lgkmcnt(0)
	ds_read_b32 v1, v192
	ds_read_b32 v2, v193
	s_waitcnt lgkmcnt(0)
	v_max_f32_e64 v2, |v2|, |v2|
	s_waitcnt vmcnt(0)
	v_add_f32_e32 v0, v0, v1
	v_mul_f32_e32 v1, 0xbfb8aa3b, v0
	v_fma_f32 v4, v0, s42, -v1
	v_rndne_f32_e32 v6, v1
	v_fmac_f32_e32 v4, 0xb2a5705f, v0
	v_sub_f32_e32 v1, v1, v6
	v_add_f32_e32 v1, v1, v4
	v_cvt_i32_f32_e32 v6, v6
	v_exp_f32_e32 v1, v1
	v_cmp_nlt_f32_e32 vcc, s43, v0
	v_ldexp_f32 v1, v1, v6
	s_nop 0
	v_cndmask_b32_e32 v1, 0, v1, vcc
	v_cmp_ngt_f32_e32 vcc, s44, v0
	s_nop 1
	v_cndmask_b32_e32 v0, v209, v1, vcc
	v_max_f32_e32 v0, v2, v0
	v_div_scale_f32 v1, s[16:17], v0, v0, 1.0
	v_rcp_f32_e32 v2, v1
	v_div_scale_f32 v4, vcc, 1.0, v0, 1.0
	v_fma_f32 v6, -v1, v2, 1.0
	v_fmac_f32_e32 v2, v6, v2
	v_mul_f32_e32 v6, v4, v2
	v_fma_f32 v24, -v1, v6, v4
	v_fmac_f32_e32 v6, v24, v2
	v_fma_f32 v1, -v1, v6, v4
	v_div_fmas_f32 v1, v1, v2, v6
	v_div_fixup_f32 v0, v1, v0, 1.0
	v_mul_f32_e32 v4, v7, v0
	v_mul_f32_e32 v6, v3, v0
	v_mul_f32_e32 v0, v4, v4
	v_fmac_f32_e32 v0, v6, v6
	ds_bpermute_b32 v1, v73, v0
	s_waitcnt lgkmcnt(0)
	v_add_f32_e32 v0, v0, v1
	ds_bpermute_b32 v1, v92, v0
	s_waitcnt lgkmcnt(0)
	v_add_f32_e32 v0, v0, v1
	ds_bpermute_b32 v1, v93, v0
	s_waitcnt lgkmcnt(0)
	v_add_f32_e32 v0, v0, v1
	ds_bpermute_b32 v1, v94, v0
	s_and_saveexec_b64 s[16:17], s[4:5]
	s_cbranch_execz .LBB0_738
	s_waitcnt lgkmcnt(0)
	v_add_f32_e32 v0, v0, v1
	ds_add_f32 v194, v0
	s_branch .LBB0_738
